# mixers queue order: pool items handed out before the rglru prompt tiles (sample-tile rglru items still first), sample-attn and rowsum last
# speedup vs baseline: 1.0038x; 1.0034x over previous
.Lq_remap:
	s_cmpk_lt_i32 s81, 0x104
	s_cselect_b32 s4, 0x182, -4
	s_cmpk_lt_i32 s81, 0x106
	s_cselect_b32 s4, s4, 0xfc
	s_cmpk_lt_i32 s81, 0x186
	s_cselect_b32 s4, s4, 0xffffff7c
	s_cmpk_lt_i32 s81, 0x286
	s_cselect_b32 s4, s4, 0
	s_add_i32 s81, s81, s4
